# Resid epilogue: 6 of the 8 second-batch residual loads issued together with the first batch (on v50)
# speedup vs baseline: 1.0091x; 1.0091x over previous
.LBB0_381:
	v_lshl_add_u32 v184, s25, 8, v167
	v_lshl_or_b32 v180, s24, 8, v202
	v_ashrrev_i32_e32 v181, 31, v180
	v_ashrrev_i32_e32 v185, 31, v184
	v_or_b32_e32 v194, 16, v184
	v_lshl_add_u64 v[182:183], v[180:181], 1, s[0:1]
	v_lshlrev_b64 v[198:199], 11, v[184:185]
	v_ashrrev_i32_e32 v195, 31, v194
	v_or_b32_e32 v190, 32, v184
	v_lshl_add_u64 v[128:129], v[182:183], 0, v[198:199]
	v_lshlrev_b64 v[196:197], 11, v[194:195]
	v_ashrrev_i32_e32 v191, 31, v190
	v_or_b32_e32 v186, 48, v184
	global_load_dwordx4 v[206:209], v[128:129], off
	global_load_dwordx4 v[152:155], v[128:129], off offset:256
	v_lshl_add_u64 v[128:129], v[182:183], 0, v[196:197]
	v_lshlrev_b64 v[192:193], 11, v[190:191]
	v_ashrrev_i32_e32 v187, 31, v186
	global_load_dwordx4 v[148:151], v[128:129], off
	global_load_dwordx4 v[144:147], v[128:129], off offset:256
	v_lshl_add_u64 v[128:129], v[182:183], 0, v[192:193]
	v_lshlrev_b64 v[188:189], 11, v[186:187]
	global_load_dwordx4 v[140:143], v[128:129], off
	global_load_dwordx4 v[136:139], v[128:129], off offset:256
	v_lshl_add_u64 v[128:129], v[182:183], 0, v[188:189]
	global_load_dwordx4 v[132:135], v[128:129], off
	s_nop 0
	global_load_dwordx4 v[128:131], v[128:129], off offset:256
	v_lshl_add_u64 v[250:251], v[182:183], 0, v[198:199]
	v_add_co_u32_e32 v250, vcc, 0x40000, v250
	s_nop 1
	v_addc_co_u32_e32 v251, vcc, 0, v251, vcc
	global_load_dwordx4 v[210:213], v[250:251], off
	global_load_dwordx4 v[222:225], v[250:251], off offset:256
	v_add_co_u32_e32 v250, vcc, 0x8000, v250
	s_nop 1
	v_addc_co_u32_e32 v251, vcc, 0, v251, vcc
	global_load_dwordx4 v[234:237], v[250:251], off
	global_load_dwordx4 v[230:233], v[250:251], off offset:256
	v_add_co_u32_e32 v250, vcc, 0x8000, v250
	s_nop 1
	v_addc_co_u32_e32 v251, vcc, 0, v251, vcc
	global_load_dwordx4 v[242:245], v[250:251], off
	global_load_dwordx4 v[246:249], v[250:251], off offset:256
	v_cndmask_b32_e64 v162, 0, 1, s[16:17]
	v_cmp_ne_u32_e64 s[40:41], 1, v162
	v_lshlrev_b64 v[162:163], 12, v[184:185]
	v_mov_b32_e32 v173, v172
	v_lshl_add_u64 v[162:163], s[12:13], 0, v[162:163]
	s_andn2_b64 vcc, exec, s[16:17]
	s_waitcnt vmcnt(0)
	v_lshlrev_b32_e32 v164, 16, v206
	v_and_b32_e32 v165, 0xffff0000, v206
	v_lshlrev_b32_e32 v200, 16, v207
	v_and_b32_e32 v201, 0xffff0000, v207
	v_lshlrev_b32_e32 v206, 16, v208
	v_and_b32_e32 v207, 0xffff0000, v208
	v_lshlrev_b32_e32 v208, 16, v209
	v_and_b32_e32 v209, 0xffff0000, v209
	v_pk_fma_f32 v[126:127], v[172:173], v[126:127], v[200:201]
	v_pk_fma_f32 v[124:125], v[174:175], v[124:125], v[164:165]
	v_pk_fma_f32 v[122:123], v[172:173], v[122:123], v[208:209]
	v_pk_fma_f32 v[120:121], v[174:175], v[120:121], v[206:207]
	v_lshl_add_u64 v[200:201], v[180:181], 2, v[162:163]
	s_cbranch_vccnz .LBB0_383
	s_mov_b64 s[82:83], 0
	global_store_dwordx4 v[200:201], v[124:127], off
	global_store_dwordx4 v[200:201], v[120:123], off offset:16
	s_branch .LBB0_384

.LBB0_415:
	s_or_b64 exec, exec, s[82:83]
	v_add_u32_e32 v104, 0x80, v184
	v_ashrrev_i32_e32 v105, 31, v104
	v_add_u32_e32 v100, 0x90, v184
	v_lshlrev_b64 v[106:107], 11, v[104:105]
	v_ashrrev_i32_e32 v101, 31, v100
	v_add_u32_e32 v96, 0xa0, v184
	s_waitcnt lgkmcnt(0)
	v_lshl_add_u64 v[64:65], v[182:183], 0, v[106:107]
	v_lshlrev_b64 v[102:103], 11, v[100:101]
	v_ashrrev_i32_e32 v97, 31, v96
	v_add_u32_e32 v92, 0xb0, v184
	v_mov_b32_e32 v108, v210
	v_mov_b32_e32 v109, v211
	v_mov_b32_e32 v110, v212
	v_mov_b32_e32 v111, v213
	v_mov_b32_e32 v88, v222
	v_mov_b32_e32 v89, v223
	v_mov_b32_e32 v90, v224
	v_mov_b32_e32 v91, v225
	v_lshl_add_u64 v[64:65], v[182:183], 0, v[102:103]
	v_lshlrev_b64 v[98:99], 11, v[96:97]
	v_ashrrev_i32_e32 v93, 31, v92
	v_mov_b32_e32 v84, v234
	v_mov_b32_e32 v85, v235
	v_mov_b32_e32 v86, v236
	v_mov_b32_e32 v87, v237
	v_mov_b32_e32 v80, v230
	v_mov_b32_e32 v81, v231
	v_mov_b32_e32 v82, v232
	v_mov_b32_e32 v83, v233
	v_lshl_add_u64 v[64:65], v[182:183], 0, v[98:99]
	v_lshlrev_b64 v[94:95], 11, v[92:93]
	v_mov_b32_e32 v76, v242
	v_mov_b32_e32 v77, v243
	v_mov_b32_e32 v78, v244
	v_mov_b32_e32 v79, v245
	v_mov_b32_e32 v72, v246
	v_mov_b32_e32 v73, v247
	v_mov_b32_e32 v74, v248
	v_mov_b32_e32 v75, v249
	v_lshl_add_u64 v[64:65], v[182:183], 0, v[94:95]
	global_load_dwordx4 v[68:71], v[64:65], off
	s_nop 0
	global_load_dwordx4 v[64:67], v[64:65], off offset:256
	v_lshlrev_b64 v[112:113], 12, v[104:105]
	v_mov_b32_e32 v173, v172
	v_lshl_add_u64 v[112:113], s[12:13], 0, v[112:113]
	s_and_b64 vcc, exec, s[40:41]
	s_waitcnt vmcnt(7)
	v_lshlrev_b32_e32 v114, 16, v108
	v_and_b32_e32 v115, 0xffff0000, v108
	v_lshlrev_b32_e32 v108, 16, v109
	v_and_b32_e32 v109, 0xffff0000, v109
	v_lshlrev_b32_e32 v116, 16, v110
	v_and_b32_e32 v117, 0xffff0000, v110
	v_lshlrev_b32_e32 v110, 16, v111
	v_and_b32_e32 v111, 0xffff0000, v111
	v_pk_fma_f32 v[62:63], v[172:173], v[62:63], v[108:109]
	v_pk_fma_f32 v[60:61], v[174:175], v[60:61], v[114:115]
	v_pk_fma_f32 v[58:59], v[172:173], v[58:59], v[110:111]
	v_pk_fma_f32 v[56:57], v[174:175], v[56:57], v[116:117]
	v_lshl_add_u64 v[108:109], v[180:181], 2, v[112:113]
	s_cbranch_vccnz .LBB0_457
	global_store_dwordx4 v[108:109], v[60:63], off
	global_store_dwordx4 v[108:109], v[56:59], off offset:16
	v_lshl_add_u64 v[106:107], s[0:1], 0, v[106:107]
	v_lshl_add_u64 v[106:107], v[180:181], 1, v[106:107]
	s_cbranch_execnz .LBB0_418
